# MoBA gate dot product: same arithmetic order without the compiler's register shuffles, four LDS reads kept in flight
# speedup vs baseline: 1.0189x; 1.0039x over previous
; #define LAS __attribute__((address_space(3)))
; __device__ __forceinline__ void moba_unit2(lbyte* lds, const bf16* QKV, bf16* AO, unsigned char* part, unsigned char* part3, const float* km2, const float* rel_bias, int b, int hm, int own) {
;     ...
;             for (int n = half; n < own; n += 2) { float g = 0.f; const LAS float* kmn = kmean + n * 64;
; #pragma unroll
;                 for (int d = 0; d < 64; d += 4) { const f32x4 kv = *(const LAS f32x4*)(kmn + d); g += q[d] * kv[0] + q[d + 1] * kv[1] + q[d + 2] * kv[2] + q[d + 3] * kv[3]; }
;                 if (g > v0) { v2 = v1; i2 = i1; v1 = v0; i1 = i0; v0 = g; i0 = n; } else if (g > v1) { v2 = v1; i2 = i1; v1 = g; i1 = n; } else if (g > v2) { v2 = g; i2 = n; } }
.LBB0_588:
	v_lshl_add_u32 v52, v74, 8, 0
	v_add_u32_e32 v54, 0x1b000, v52
	ds_read_b128 v[80:83], v54
	ds_read_b128 v[84:87], v54 offset:16
	ds_read_b128 v[88:91], v54 offset:32
	ds_read_b128 v[92:95], v54 offset:48
	s_waitcnt lgkmcnt(3)
	v_mul_f32_e32 v52, v81, v59
	v_fmac_f32_e32 v52, v80, v58
	v_fmac_f32_e32 v52, v82, v60
	v_fmac_f32_e32 v52, v83, v61
	ds_read_b128 v[80:83], v54 offset:64
	v_add_f32_e32 v52, 0, v52
	s_waitcnt lgkmcnt(3)
	v_mul_f32_e32 v53, v85, v63
	v_fmac_f32_e32 v53, v84, v62
	v_fmac_f32_e32 v53, v86, v64
	v_fmac_f32_e32 v53, v87, v65
	ds_read_b128 v[84:87], v54 offset:80
	v_add_f32_e32 v52, v52, v53
	s_waitcnt lgkmcnt(3)
	v_mul_f32_e32 v53, v89, v67
	v_fmac_f32_e32 v53, v88, v66
	v_fmac_f32_e32 v53, v90, v68
	v_fmac_f32_e32 v53, v91, v69
	ds_read_b128 v[88:91], v54 offset:96
	v_add_f32_e32 v52, v52, v53
	s_waitcnt lgkmcnt(3)
	v_mul_f32_e32 v53, v93, v71
	v_fmac_f32_e32 v53, v92, v70
	v_fmac_f32_e32 v53, v94, v72
	v_fmac_f32_e32 v53, v95, v73
	ds_read_b128 v[92:95], v54 offset:112
	v_add_f32_e32 v57, v52, v53
	s_waitcnt lgkmcnt(2)
	v_mul_f32_e32 v52, v81, v6
	v_mul_f32_e32 v53, v85, v7
	v_fmac_f32_e32 v52, v80, v4
	v_fmac_f32_e32 v53, v84, v5
	v_fmac_f32_e32 v52, v82, v8
	v_fmac_f32_e32 v53, v86, v9
	v_fmac_f32_e32 v52, v83, v10
	v_fmac_f32_e32 v53, v87, v11
	ds_read_b128 v[80:83], v54 offset:128
	ds_read_b128 v[84:87], v54 offset:144
	v_add_f32_e32 v52, v57, v52
	v_add_f32_e32 v57, v52, v53
	s_waitcnt lgkmcnt(2)
	v_mul_f32_e32 v52, v89, v14
	v_mul_f32_e32 v53, v93, v15
	v_fmac_f32_e32 v52, v88, v12
	v_fmac_f32_e32 v53, v92, v13
	v_fmac_f32_e32 v52, v90, v16
	v_fmac_f32_e32 v53, v94, v17
	v_fmac_f32_e32 v52, v91, v18
	v_fmac_f32_e32 v53, v95, v19
	ds_read_b128 v[88:91], v54 offset:160
	ds_read_b128 v[92:95], v54 offset:176
	v_add_f32_e32 v52, v57, v52
	v_add_f32_e32 v57, v52, v53
	s_waitcnt lgkmcnt(2)
	v_mul_f32_e32 v52, v81, v22
	v_mul_f32_e32 v53, v85, v23
	v_fmac_f32_e32 v52, v80, v20
	v_fmac_f32_e32 v53, v84, v21
	v_fmac_f32_e32 v52, v82, v24
	v_fmac_f32_e32 v53, v86, v25
	v_fmac_f32_e32 v52, v83, v26
	v_fmac_f32_e32 v53, v87, v27
	ds_read_b128 v[80:83], v54 offset:192
	ds_read_b128 v[84:87], v54 offset:208
	v_add_f32_e32 v52, v57, v52
	v_add_f32_e32 v57, v52, v53
	s_waitcnt lgkmcnt(2)
	v_mul_f32_e32 v52, v89, v30
	v_mul_f32_e32 v53, v93, v31
	v_fmac_f32_e32 v52, v88, v28
	v_fmac_f32_e32 v53, v92, v29
	v_fmac_f32_e32 v52, v90, v32
	v_fmac_f32_e32 v53, v94, v33
	v_fmac_f32_e32 v52, v91, v34
	v_fmac_f32_e32 v53, v95, v35
	ds_read_b128 v[88:91], v54 offset:224
	ds_read_b128 v[92:95], v54 offset:240
	v_add_f32_e32 v52, v57, v52
	v_add_f32_e32 v57, v52, v53
	s_waitcnt lgkmcnt(2)
	v_mul_f32_e32 v52, v81, v38
	v_mul_f32_e32 v53, v85, v39
	v_fmac_f32_e32 v52, v80, v36
	v_fmac_f32_e32 v53, v84, v37
	v_fmac_f32_e32 v52, v82, v40
	v_fmac_f32_e32 v53, v86, v41
	v_fmac_f32_e32 v52, v83, v42
	v_fmac_f32_e32 v53, v87, v43
	v_add_f32_e32 v52, v57, v52
	v_add_f32_e32 v79, v52, v53
	s_waitcnt lgkmcnt(0)
	v_mul_f32_e32 v52, v89, v46
	v_mul_f32_e32 v53, v93, v47
	v_fmac_f32_e32 v52, v88, v44
	v_fmac_f32_e32 v53, v92, v45
	v_fmac_f32_e32 v52, v90, v48
	v_fmac_f32_e32 v53, v94, v49
	v_fmac_f32_e32 v52, v91, v50
	v_fmac_f32_e32 v53, v95, v51
	v_add_f32_e32 v52, v79, v52
	v_add_f32_e32 v54, v52, v53
	v_cmp_ngt_f32_e32 vcc, v54, v76
	v_mov_b32_e32 v53, v74
	s_and_saveexec_b64 s[22:23], vcc
	s_cbranch_execz .LBB0_587
	v_cmp_ngt_f32_e32 vcc, v54, v75
	v_mov_b32_e32 v52, v74
	s_and_saveexec_b64 s[24:25], vcc
	s_cbranch_execz .LBB0_586
	v_cmp_gt_f32_e32 vcc, v54, v3
	s_and_saveexec_b64 s[26:27], vcc
	s_cbranch_execz .LBB0_585
	v_mov_b32_e32 v3, v54
	v_mov_b32_e32 v0, v74
	s_branch .LBB0_585
